# v029 minus the two s_nop 7/s_nop 3 hazard pads in the attention loop (the restructured path already puts 30+ issue slots between the last QK^T MFMA and the first VALU read of its result)
# baseline (speedup 1.0000x reference)
.Lattn_h1_join:
	s_mov_b32 s10, 0xffe80000
	v_add_co_u32_e32 v6, vcc, s10, v178
	s_mov_b32 s10, 0xfff00000
	s_nop 0
	v_addc_co_u32_e32 v7, vcc, -1, v179, vcc
	v_add_co_u32_e32 v30, vcc, s10, v178
	s_nop 1
	v_addc_co_u32_e32 v31, vcc, -1, v179, vcc
	global_load_dwordx4 v[2:5], v[6:7], off
	s_nop 0
	global_load_dwordx4 v[6:9], v[6:7], off offset:-256
	s_nop 0
	global_load_dwordx4 v[10:13], v[30:31], off
	global_load_dwordx4 v[160:163], v[30:31], off offset:-256
	v_add_co_u32_e32 v30, vcc, 0xffffe000, v176
	s_nop 1
	v_addc_co_u32_e32 v31, vcc, -1, v177, vcc
	global_load_dwordx4 v[164:167], v[30:31], off
	s_cmp_le_i32 s54, s4
	s_cbranch_scc1 .Lh1_nomask
	v_add_u32_e32 v15, 0x4000007b, v210
	v_cmp_gt_u32_e32 vcc, 2.0, v15
	v_add_u32_e32 v15, 0x5b, v210
	s_nop 0
	v_cndmask_b32_e32 v112, v16, v112, vcc
	v_cmp_lt_u32_e32 vcc, s85, v15
	v_add_u32_e32 v15, 0x7a, v210
	s_nop 0
	v_cndmask_b32_e32 v96, v16, v96, vcc
	v_cmp_lt_u32_e32 vcc, s85, v15
	v_add_u32_e32 v15, 0x5a, v210
	s_nop 0
	v_cndmask_b32_e32 v113, v16, v113, vcc
	v_cmp_lt_u32_e32 vcc, s85, v15
	v_add_u32_e32 v15, 0x79, v210
	s_nop 0
	v_cndmask_b32_e32 v97, v16, v97, vcc
	v_cmp_lt_u32_e32 vcc, s85, v15
	v_add_u32_e32 v15, 0x59, v210
	s_nop 0
	v_cndmask_b32_e32 v114, v16, v114, vcc
	v_cmp_lt_u32_e32 vcc, s85, v15
	v_add_u32_e32 v15, 0x78, v210
	s_nop 0
	v_cndmask_b32_e32 v98, v16, v98, vcc
	v_cmp_lt_u32_e32 vcc, s85, v15
	v_add_u32_e32 v15, 0x58, v210
	s_nop 0
	v_cndmask_b32_e32 v115, v16, v115, vcc
	v_cmp_lt_u32_e32 vcc, s85, v15
	v_add_u32_e32 v15, 0x73, v210
	s_nop 0
	v_cndmask_b32_e32 v99, v16, v99, vcc
	v_cmp_lt_u32_e32 vcc, s85, v15
	v_add_u32_e32 v15, 0x53, v210
	s_nop 0
	v_cndmask_b32_e32 v116, v16, v116, vcc
	v_cmp_lt_u32_e32 vcc, s85, v15
	v_add_u32_e32 v15, 0x72, v210
	s_nop 0
	v_cndmask_b32_e32 v100, v16, v100, vcc
	v_cmp_lt_u32_e32 vcc, s85, v15
	v_add_u32_e32 v15, 0x52, v210
	s_nop 0
	v_cndmask_b32_e32 v117, v16, v117, vcc
	v_cmp_lt_u32_e32 vcc, s85, v15
	v_add_u32_e32 v15, 0x71, v210
	s_nop 0
	v_cndmask_b32_e32 v101, v16, v101, vcc
	v_cmp_lt_u32_e32 vcc, s85, v15
	v_add_u32_e32 v15, 0x51, v210
	s_nop 0
	v_cndmask_b32_e32 v118, v16, v118, vcc
	v_cmp_lt_u32_e32 vcc, s85, v15
	v_add_u32_e32 v15, 0x70, v210
	s_nop 0
	v_cndmask_b32_e32 v102, v16, v102, vcc
	v_cmp_lt_u32_e32 vcc, s85, v15
	v_add_u32_e32 v15, 0x50, v210
	s_nop 0
	v_cndmask_b32_e32 v119, v16, v119, vcc
	v_cmp_lt_u32_e32 vcc, s85, v15
	v_add_u32_e32 v15, 0x6b, v210
	s_nop 0
	v_cndmask_b32_e32 v103, v16, v103, vcc
	v_cmp_lt_u32_e32 vcc, s85, v15
	v_add_u32_e32 v15, 0x4b, v210
	s_nop 0
	v_cndmask_b32_e32 v120, v16, v120, vcc
	v_cmp_lt_u32_e32 vcc, s85, v15
	v_add_u32_e32 v15, 0x6a, v210
	s_nop 0
	v_cndmask_b32_e32 v104, v16, v104, vcc
	v_cmp_lt_u32_e32 vcc, s85, v15
	v_add_u32_e32 v15, 0x4a, v210
	s_nop 0
	v_cndmask_b32_e32 v121, v16, v121, vcc
	v_cmp_lt_u32_e32 vcc, s85, v15
	v_add_u32_e32 v15, 0x69, v210
	s_nop 0
	v_cndmask_b32_e32 v105, v16, v105, vcc
	v_cmp_lt_u32_e32 vcc, s85, v15
	v_add_u32_e32 v15, 0x49, v210
	s_nop 0
	v_cndmask_b32_e32 v122, v16, v122, vcc
	v_cmp_lt_u32_e32 vcc, s85, v15
	v_add_u32_e32 v15, 0x68, v210
	s_nop 0
	v_cndmask_b32_e32 v106, v16, v106, vcc
	v_cmp_lt_u32_e32 vcc, s85, v15
	v_add_u32_e32 v15, 0x48, v210
	s_nop 0
	v_cndmask_b32_e32 v123, v16, v123, vcc
	v_cmp_lt_u32_e32 vcc, s85, v15
	v_add_u32_e32 v15, 0x63, v210
	s_nop 0
	v_cndmask_b32_e32 v107, v16, v107, vcc
	v_cmp_lt_u32_e32 vcc, s85, v15
	v_add_u32_e32 v15, 0x43, v210
	s_nop 0
	v_cndmask_b32_e32 v124, v16, v124, vcc
	v_cmp_lt_u32_e32 vcc, s85, v15
	v_add_u32_e32 v15, 0x62, v210
	s_nop 0
	v_cndmask_b32_e32 v108, v16, v108, vcc
	v_cmp_lt_u32_e32 vcc, s85, v15
	v_add_u32_e32 v15, 0x42, v210
	s_nop 0
	v_cndmask_b32_e32 v125, v16, v125, vcc
	v_cmp_lt_u32_e32 vcc, s85, v15
	v_add_u32_e32 v15, 0x61, v210
	s_nop 0
	v_cndmask_b32_e32 v109, v16, v109, vcc
	v_cmp_lt_u32_e32 vcc, s85, v15
	v_add_u32_e32 v15, 0x41, v210
	s_nop 0
	v_cndmask_b32_e32 v126, v16, v126, vcc
	v_cmp_lt_u32_e32 vcc, s85, v15
	v_add_u32_e32 v15, 0x60, v210
	s_nop 0
	v_cndmask_b32_e32 v110, v16, v110, vcc
	v_cmp_lt_u32_e32 vcc, s85, v15
	v_add_u32_e32 v15, 64, v210
	s_nop 0
	v_cndmask_b32_e32 v127, v16, v127, vcc
	v_cmp_lt_u32_e32 vcc, s85, v15
	s_nop 1
	v_cndmask_b32_e32 v111, v16, v111, vcc

.Lh2_noload:
	s_add_i32 s10, s54, 64
	s_cmp_le_i32 s10, s4
	s_cbranch_scc1 .Lh2_nomask
	v_add_u32_e32 v255, 0x4000003b, v210
	v_cmp_gt_u32_e32 vcc, 2.0, v255
	v_add_u32_e32 v255, 27, v210
	s_nop 0
	v_cndmask_b32_e32 v112, v16, v112, vcc
	v_cmp_lt_u32_e32 vcc, s85, v255
	v_add_u32_e32 v255, 58, v210
	s_nop 0
	v_cndmask_b32_e32 v96, v16, v96, vcc
	v_cmp_lt_u32_e32 vcc, s85, v255
	v_add_u32_e32 v255, 26, v210
	s_nop 0
	v_cndmask_b32_e32 v113, v16, v113, vcc
	v_cmp_lt_u32_e32 vcc, s85, v255
	v_add_u32_e32 v255, 57, v210
	s_nop 0
	v_cndmask_b32_e32 v97, v16, v97, vcc
	v_cmp_lt_u32_e32 vcc, s85, v255
	v_add_u32_e32 v255, 25, v210
	s_nop 0
	v_cndmask_b32_e32 v114, v16, v114, vcc
	v_cmp_lt_u32_e32 vcc, s85, v255
	v_add_u32_e32 v255, 56, v210
	s_nop 0
	v_cndmask_b32_e32 v98, v16, v98, vcc
	v_cmp_lt_u32_e32 vcc, s85, v255
	v_add_u32_e32 v255, 24, v210
	s_nop 0
	v_cndmask_b32_e32 v115, v16, v115, vcc
	v_cmp_lt_u32_e32 vcc, s85, v255
	v_add_u32_e32 v255, 51, v210
	s_nop 0
	v_cndmask_b32_e32 v99, v16, v99, vcc
	v_cmp_lt_u32_e32 vcc, s85, v255
	v_add_u32_e32 v255, 19, v210
	s_nop 0
	v_cndmask_b32_e32 v116, v16, v116, vcc
	v_cmp_lt_u32_e32 vcc, s85, v255
	v_add_u32_e32 v255, 50, v210
	s_nop 0
	v_cndmask_b32_e32 v100, v16, v100, vcc
	v_cmp_lt_u32_e32 vcc, s85, v255
	v_add_u32_e32 v255, 18, v210
	s_nop 0
	v_cndmask_b32_e32 v117, v16, v117, vcc
	v_cmp_lt_u32_e32 vcc, s85, v255
	v_add_u32_e32 v255, 49, v210
	s_nop 0
	v_cndmask_b32_e32 v101, v16, v101, vcc
	v_cmp_lt_u32_e32 vcc, s85, v255
	v_add_u32_e32 v255, 17, v210
	s_nop 0
	v_cndmask_b32_e32 v118, v16, v118, vcc
	v_cmp_lt_u32_e32 vcc, s85, v255
	v_add_u32_e32 v255, 48, v210
	s_nop 0
	v_cndmask_b32_e32 v102, v16, v102, vcc
	v_cmp_lt_u32_e32 vcc, s85, v255
	v_add_u32_e32 v255, 16, v210
	s_nop 0
	v_cndmask_b32_e32 v119, v16, v119, vcc
	v_cmp_lt_u32_e32 vcc, s85, v255
	v_add_u32_e32 v255, 43, v210
	s_nop 0
	v_cndmask_b32_e32 v103, v16, v103, vcc
	v_cmp_lt_u32_e32 vcc, s85, v255
	v_add_u32_e32 v255, 11, v210
	s_nop 0
	v_cndmask_b32_e32 v120, v16, v120, vcc
	v_cmp_lt_u32_e32 vcc, s85, v255
	v_add_u32_e32 v255, 42, v210
	s_nop 0
	v_cndmask_b32_e32 v104, v16, v104, vcc
	v_cmp_lt_u32_e32 vcc, s85, v255
	v_add_u32_e32 v255, 10, v210
	s_nop 0
	v_cndmask_b32_e32 v121, v16, v121, vcc
	v_cmp_lt_u32_e32 vcc, s85, v255
	v_add_u32_e32 v255, 41, v210
	s_nop 0
	v_cndmask_b32_e32 v105, v16, v105, vcc
	v_cmp_lt_u32_e32 vcc, s85, v255
	v_add_u32_e32 v255, 9, v210
	s_nop 0
	v_cndmask_b32_e32 v122, v16, v122, vcc
	v_cmp_lt_u32_e32 vcc, s85, v255
	v_add_u32_e32 v255, 40, v210
	s_nop 0
	v_cndmask_b32_e32 v106, v16, v106, vcc
	v_cmp_lt_u32_e32 vcc, s85, v255
	v_add_u32_e32 v255, 8, v210
	s_nop 0
	v_cndmask_b32_e32 v123, v16, v123, vcc
	v_cmp_lt_u32_e32 vcc, s85, v255
	v_add_u32_e32 v255, 35, v210
	s_nop 0
	v_cndmask_b32_e32 v107, v16, v107, vcc
	v_cmp_lt_u32_e32 vcc, s85, v255
	v_add_u32_e32 v255, 3, v210
	s_nop 0
	v_cndmask_b32_e32 v124, v16, v124, vcc
	v_cmp_lt_u32_e32 vcc, s85, v255
	v_add_u32_e32 v255, 34, v210
	s_nop 0
	v_cndmask_b32_e32 v108, v16, v108, vcc
	v_cmp_lt_u32_e32 vcc, s85, v255
	v_add_u32_e32 v255, 2, v210
	s_nop 0
	v_cndmask_b32_e32 v125, v16, v125, vcc
	v_cmp_lt_u32_e32 vcc, s85, v255
	v_add_u32_e32 v255, 33, v210
	s_nop 0
	v_cndmask_b32_e32 v109, v16, v109, vcc
	v_cmp_lt_u32_e32 vcc, s85, v255
	v_add_u32_e32 v255, 1, v210
	s_nop 0
	v_cndmask_b32_e32 v126, v16, v126, vcc
	v_cmp_lt_u32_e32 vcc, s85, v255
	v_add_u32_e32 v255, 32, v210
	s_nop 0
	v_cndmask_b32_e32 v110, v16, v110, vcc
	v_cmp_lt_u32_e32 vcc, s85, v255
	s_nop 1
	v_cndmask_b32_e32 v127, v16, v127, vcc
	v_cmp_lt_u32_e32 vcc, s85, v210
	s_nop 1
	v_cndmask_b32_e32 v111, v16, v111, vcc
